# prep: weight-transpose tiles rebalanced onto half-blocks without s5_gen (12/20/0 tiles); plus pipelined GLA state fold with coalesced sloc layout, s5_y epilogue prefetch
# speedup vs baseline: 1.0182x; 1.0182x over previous
.LBB0_52:
	v_writelane_b32 v253, s24, 58
	s_nop 1
	v_writelane_b32 v253, s25, 59
	s_or_b64 exec, exec, s[8:9]
	s_load_dwordx16 s[4:19], s[0:1], 0x80
	s_load_dwordx16 s[56:71], s[0:1], 0x138
	s_waitcnt lgkmcnt(0)
	v_writelane_b32 v253, s4, 60
	s_nop 1
	v_writelane_b32 v254, s8, 0
	v_writelane_b32 v254, s9, 1
	v_writelane_b32 v254, s10, 2
	v_writelane_b32 v254, s11, 3
	v_writelane_b32 v254, s12, 4
	v_writelane_b32 v254, s13, 5
	v_writelane_b32 v254, s14, 6
	v_writelane_b32 v254, s15, 7
	v_writelane_b32 v254, s16, 8
	v_writelane_b32 v253, s5, 61
	v_writelane_b32 v254, s17, 9
	v_writelane_b32 v253, s6, 62
	v_writelane_b32 v254, s18, 10
	v_writelane_b32 v253, s7, 63
	v_writelane_b32 v254, s19, 11
	s_load_dwordx16 s[4:19], s[0:1], 0xc0
	v_readlane_b32 s24, v253, 18
	v_readlane_b32 s25, v253, 19
	v_readlane_b32 s26, v253, 20
	v_readlane_b32 s27, v253, 21
	s_waitcnt lgkmcnt(0)
	v_writelane_b32 v254, s4, 12
	v_readlane_b32 s28, v253, 22
	v_readlane_b32 s29, v253, 23
	v_writelane_b32 v254, s5, 13
	v_writelane_b32 v254, s6, 14
	v_writelane_b32 v254, s7, 15
	v_writelane_b32 v254, s8, 16
	v_writelane_b32 v254, s9, 17
	v_writelane_b32 v254, s10, 18
	v_writelane_b32 v254, s11, 19
	v_writelane_b32 v254, s12, 20
	v_writelane_b32 v254, s13, 21
	v_writelane_b32 v254, s14, 22
	v_writelane_b32 v254, s15, 23
	v_writelane_b32 v254, s16, 24
	v_writelane_b32 v254, s17, 25
	v_writelane_b32 v254, s18, 26
	v_writelane_b32 v254, s19, 27
	s_mov_b64 s[4:5], s[76:77]
	s_mov_b64 s[12:13], s[84:85]
	s_mov_b64 s[6:7], s[78:79]
	s_mov_b64 s[14:15], s[86:87]
	s_mov_b64 s[10:11], s[82:83]
	s_mov_b64 s[18:19], s[90:91]
	v_readlane_b32 s30, v253, 24
	v_readlane_b32 s31, v253, 25
	v_writelane_b32 v253, s4, 42
	v_readfirstlane_b32 s0, v234
	s_lshr_b32 s0, s0, 8
	v_writelane_b32 v253, s5, 43
	v_writelane_b32 v253, s6, 44
	v_writelane_b32 v253, s7, 45
	v_writelane_b32 v253, s8, 46
	v_writelane_b32 v253, s9, 47
	v_writelane_b32 v253, s10, 48
	v_writelane_b32 v253, s11, 49
	v_writelane_b32 v253, s12, 50
	v_writelane_b32 v253, s13, 51
	v_writelane_b32 v253, s14, 52
	v_writelane_b32 v253, s15, 53
	v_writelane_b32 v253, s16, 54
	v_writelane_b32 v253, s17, 55
	s_add_i32 s40, s0, s92
	s_lshl_b32 s93, s30, 1
	v_writelane_b32 v253, s18, 56
	v_writelane_b32 v253, s19, 57
	s_movk_i32 s98, 0xc0
	s_movk_i32 s99, 0x900
	s_cmpk_lt_u32 s40, 0xc0
	s_cbranch_scc1 .Ltr_go
	s_cmpk_gt_u32 s40, 0xff
	s_cbranch_scc1 .LBB0_104
	s_addk_i32 s40, 0x840
	s_movk_i32 s98, 0x40
	s_movk_i32 s99, 0xe00
.Ltr_go:
	s_lshl_b32 s41, s40, 3
	s_lshl_b32 s42, s98, 3
	s_lshl_b32 s43, s40, 6
	s_lshl_b32 s44, s98, 6
	s_lshl_b32 s45, s40, 2
	s_lshl_b32 s46, s98, 2
	s_mov_b32 s1, 0
	v_mov_b32_e32 v3, 0
	s_movk_i32 s47, 0x4000
	s_mov_b32 s48, 0x8000
	s_mov_b32 s49, 0xc000
	s_mov_b32 s50, 0x10000
	s_mov_b32 s51, 0x14000
	s_mov_b32 s52, 0x18000
	s_mov_b32 s53, 0x1c000
	s_mov_b32 s54, 0x20000
	s_mov_b32 s55, 0x24000
	s_mov_b32 s73, 0x28000
	s_mov_b32 s74, 0x2c000
	s_mov_b32 s75, 0x30000
	s_mov_b32 s76, 0x34000
	s_mov_b32 s77, 0x38000
	s_mov_b32 s78, 0x3c000
	s_movk_i32 s79, 0x104
	s_movk_i32 s80, 0x4840
	s_branch .LBB0_56

.LBB0_55:
	s_add_i32 s40, s40, s98
	s_add_i32 s41, s41, s42
	s_add_i32 s43, s43, s44
	s_add_i32 s45, s45, s46
	s_cmp_lt_i32 s40, s99
	s_cbranch_scc0 .LBB0_103

.LBB0_542:
	s_lshl_b32 s10, s50, 5
	s_add_i32 s10, s10, s52
	s_or_b32 s10, s10, s53
	s_lshl_b32 s10, s10, 1
	s_or_b32 s12, s10, s46
	s_ashr_i32 s13, s12, 31
	v_readlane_b32 s80, v253, 8
	s_lshl_b64 s[36:37], s[12:13], 15
	v_readlane_b32 s86, v253, 14
	v_readlane_b32 s87, v253, 15
	s_add_u32 s36, s86, s36
	s_addc_u32 s37, s87, s37
	v_readlane_b32 s81, v253, 9
	v_readlane_b32 s82, v253, 10
	v_readlane_b32 s83, v253, 11
	v_readlane_b32 s84, v253, 12
	v_readlane_b32 s85, v253, 13
	v_lshrrev_b32_e32 v0, 6, v235
	v_and_b32_e32 v1, 63, v235
	v_lshlrev_b32_e32 v0, 13, v0
	v_lshl_or_b32 v0, v1, 4, v0
	v_add_u32_e32 v1, 0x1000, v0
	global_store_dwordx2 v0, v[70:71], s[36:37]
	global_store_dwordx2 v0, v[68:69], s[36:37] offset:8
	global_store_dwordx2 v0, v[64:65], s[36:37] offset:1024
	global_store_dwordx2 v0, v[62:63], s[36:37] offset:1032
	global_store_dwordx2 v0, v[60:61], s[36:37] offset:2048
	global_store_dwordx2 v0, v[58:59], s[36:37] offset:2056
	global_store_dwordx2 v0, v[56:57], s[36:37] offset:3072
	global_store_dwordx2 v0, v[52:53], s[36:37] offset:3080
	global_store_dwordx2 v1, v[54:55], s[36:37]
	global_store_dwordx2 v1, v[50:51], s[36:37] offset:8
	global_store_dwordx2 v1, v[48:49], s[36:37] offset:1024
	global_store_dwordx2 v1, v[46:47], s[36:37] offset:1032
	global_store_dwordx2 v1, v[44:45], s[36:37] offset:2048
	global_store_dwordx2 v1, v[40:41], s[36:37] offset:2056
	global_store_dwordx2 v1, v[38:39], s[36:37] offset:3072
	global_store_dwordx2 v1, v[36:37], s[36:37] offset:3080
	s_and_saveexec_b64 s[36:37], s[2:3]
	s_cbranch_execz .LBB0_523
	v_mul_f32_e32 v0, 0x3fb8aa3b, v82
	v_exp_f32_e32 v0, v0
	s_lshl_b64 s[2:3], s[12:13], 8
	v_readlane_b32 s8, v253, 18
	v_readlane_b32 s9, v253, 19
	s_add_u32 s2, s8, s2
	s_addc_u32 s3, s9, s3
	v_readlane_b32 s10, v253, 20
	v_readlane_b32 s11, v253, 21
	v_readlane_b32 s12, v253, 22
	v_readlane_b32 s13, v253, 23
	v_readlane_b32 s14, v253, 24
	v_readlane_b32 s15, v253, 25
	global_store_dword v192, v0, s[2:3]
	s_branch .LBB0_523

.LBB0_623:
	v_readlane_b32 s16, v253, 26
	s_bfe_u32 s80, s8, 0x20001
	v_ashrrev_i32_e32 v196, 6, v195
	v_readlane_b32 s22, v253, 32
	v_readlane_b32 s23, v253, 33
	v_and_b32_e32 v197, 31, v195
	v_bfe_u32 v190, v195, 5, 1
	s_waitcnt vmcnt(34)
	v_lshlrev_b32_e32 v16, 5, v196
	s_lshl_b32 s2, s80, 6
	s_lshl_b32 s90, s80, 8
	s_mov_b64 s[14:15], s[22:23]
	v_and_or_b32 v199, v16, 32, v197
	v_lshlrev_b32_e32 v198, 3, v190
	s_add_u32 s40, s14, s90
	v_or_b32_e32 v0, s86, v198
	s_addc_u32 s41, s15, 0
	v_lshlrev_b32_e32 v192, 2, v199
	v_lshl_add_u64 v[2:3], s[40:41], 0, v[192:193]
	v_or_b32_e32 v192, 2, v0
	v_lshlrev_b64 v[8:9], 10, v[192:193]
	v_lshlrev_b64 v[10:11], 8, v[192:193]
	v_or_b32_e32 v192, 4, v0
	v_mov_b32_e32 v1, v193
	v_lshlrev_b64 v[12:13], 10, v[192:193]
	v_lshlrev_b64 v[14:15], 8, v[192:193]
	v_or_b32_e32 v192, 6, v0
	v_lshlrev_b64 v[4:5], 10, v[0:1]
	v_lshlrev_b64 v[6:7], 8, v[0:1]
	v_lshlrev_b64 v[0:1], 10, v[192:193]
	v_lshl_add_u64 v[4:5], v[2:3], 0, v[4:5]
	v_lshl_add_u64 v[8:9], v[2:3], 0, v[8:9]
	v_lshl_add_u64 v[12:13], v[2:3], 0, v[12:13]
	v_lshl_add_u64 v[0:1], v[2:3], 0, v[0:1]
	v_lshlrev_b64 v[2:3], 8, v[192:193]
	v_or3_b32 v6, v6, v199, s2
	v_or3_b32 v10, v10, v199, s2
	v_or3_b32 v14, v14, v199, s2
	v_or3_b32 v2, v2, v199, s2
	v_lshlrev_b64 v[6:7], 2, v[6:7]
	v_lshlrev_b64 v[10:11], 2, v[10:11]
	v_lshlrev_b64 v[14:15], 2, v[14:15]
	v_lshlrev_b64 v[2:3], 2, v[2:3]
	v_or_b32_e32 v6, 0x400, v6
	v_or_b32_e32 v10, 0x400, v10
	v_or_b32_e32 v14, 0x400, v14
	v_or_b32_e32 v2, 0x400, v2
	v_lshl_add_u64 v[6:7], s[14:15], 0, v[6:7]
	v_lshl_add_u64 v[10:11], s[14:15], 0, v[10:11]
	v_lshl_add_u64 v[14:15], s[14:15], 0, v[14:15]
	v_lshl_add_u64 v[2:3], s[14:15], 0, v[2:3]
	global_load_dword v200, v[4:5], off
	global_load_dword v201, v[6:7], off
	global_load_dword v202, v[8:9], off
	global_load_dword v203, v[10:11], off
	global_load_dword v204, v[12:13], off
	global_load_dword v205, v[14:15], off
	global_load_dword v206, v[0:1], off
	global_load_dword v207, v[2:3], off
	v_readlane_b32 s17, v253, 27
	v_readlane_b32 s18, v253, 28
	v_readlane_b32 s19, v253, 29
	v_readlane_b32 s20, v253, 30
	v_readlane_b32 s21, v253, 31
	v_readlane_b32 s24, v253, 34
	v_readlane_b32 s25, v253, 35
	s_or_b32 s3, s2, s87
	v_readlane_b32 s26, v253, 36
	v_readlane_b32 s27, v253, 37
	v_readlane_b32 s28, v253, 38
	v_readlane_b32 s29, v253, 39
	v_readlane_b32 s30, v253, 40
	v_readlane_b32 s31, v253, 41
	s_mov_b64 s[16:17], s[24:25]
	v_or_b32_e32 v192, s3, v199
	v_lshl_add_u64 v[0:1], v[192:193], 2, s[16:17]
	global_load_dword v191, v[0:1], off
	s_waitcnt vmcnt(16)
	v_mov_b32_e32 v74, 0
	v_or_b32_e32 v72, v16, v197
	s_andn2_b64 vcc, exec, s[0:1]
	v_mov_b32_e32 v75, v74
	s_waitcnt vmcnt(14)
	v_mov_b32_e32 v76, v74
	v_mov_b32_e32 v77, v74
	v_mov_b32_e32 v78, v74
	v_mov_b32_e32 v79, v74
	s_waitcnt vmcnt(12)
	v_mov_b32_e32 v80, v74
	v_mov_b32_e32 v81, v74
	v_mov_b32_e32 v82, v74
	v_mov_b32_e32 v83, v74
	v_mov_b32_e32 v84, v74
	v_mov_b32_e32 v85, v74
	v_mov_b32_e32 v86, v74
	v_mov_b32_e32 v87, v74
	v_mov_b32_e32 v88, v74
	v_mov_b32_e32 v89, v74
	v_mov_b32_e32 v90, v74
	v_mov_b32_e32 v91, v74
	s_waitcnt vmcnt(11)
	v_mov_b32_e32 v92, v74
	v_mov_b32_e32 v93, v74
	v_mov_b32_e32 v94, v74
	v_mov_b32_e32 v95, v74
	v_mov_b32_e32 v96, v74
	v_mov_b32_e32 v97, v74
	v_mov_b32_e32 v98, v74
	v_mov_b32_e32 v99, v74
	v_mov_b32_e32 v100, v74
	v_mov_b32_e32 v101, v74
	v_mov_b32_e32 v102, v74
	v_mov_b32_e32 v103, v74
	v_mov_b32_e32 v104, v74
	v_mov_b32_e32 v105, v74
	s_mov_b64 s[18:19], s[26:27]
	s_mov_b64 s[20:21], s[28:29]
	s_mov_b64 s[22:23], s[30:31]
	s_cbranch_vccnz .LBB0_629
	s_lshl_b32 s0, s78, 4
	v_readlane_b32 s1, v255, 55
	s_or_b32 s0, s0, s1
	s_or_b32 s0, s0, s80
	s_ashr_i32 s1, s0, 31
	v_readlane_b32 s16, v253, 42
	s_lshl_b64 s[0:1], s[0:1], 15
	v_readlane_b32 s26, v253, 52
	v_lshlrev_b32_e32 v32, 9, v190
	v_readlane_b32 s27, v253, 53
	s_add_u32 s0, s26, s0
	v_add_u32_e32 v0, v72, v32
	s_addc_u32 s1, s27, s1
	v_ashrrev_i32_e32 v1, 31, v0
	v_lshl_add_u64 v[2:3], v[0:1], 2, s[0:1]
	v_add_u32_e32 v4, 0x400, v0
	s_movk_i32 s3, 0x4000
	global_load_dword v74, v[2:3], off
	global_load_dword v75, v[2:3], off offset:512
	global_load_dword v76, v[2:3], off offset:1024
	global_load_dword v77, v[2:3], off offset:1536
	v_ashrrev_i32_e32 v5, 31, v4
	v_add_co_u32_e32 v2, vcc, s3, v2
	v_lshl_add_u64 v[4:5], v[4:5], 2, s[0:1]
	s_nop 0
	v_addc_co_u32_e32 v3, vcc, 0, v3, vcc
	global_load_dword v78, v[4:5], off
	global_load_dword v90, v[2:3], off
	v_add_u32_e32 v4, 0x480, v0
	v_add_u32_e32 v2, 0x1080, v0
	v_ashrrev_i32_e32 v5, 31, v4
	v_ashrrev_i32_e32 v3, 31, v2
	v_lshl_add_u64 v[4:5], v[4:5], 2, s[0:1]
	v_lshl_add_u64 v[2:3], v[2:3], 2, s[0:1]
	global_load_dword v79, v[4:5], off
	global_load_dword v91, v[2:3], off
	v_add_u32_e32 v4, 0x500, v0
	v_add_u32_e32 v2, 0x1100, v0
	v_ashrrev_i32_e32 v5, 31, v4
	v_ashrrev_i32_e32 v3, 31, v2
	v_lshl_add_u64 v[4:5], v[4:5], 2, s[0:1]
	v_lshl_add_u64 v[2:3], v[2:3], 2, s[0:1]
	global_load_dword v80, v[4:5], off
	global_load_dword v92, v[2:3], off
	v_add_u32_e32 v4, 0x580, v0
	v_add_u32_e32 v2, 0x1180, v0
	v_ashrrev_i32_e32 v5, 31, v4
	v_ashrrev_i32_e32 v3, 31, v2
	v_lshl_add_u64 v[4:5], v[4:5], 2, s[0:1]
	v_lshl_add_u64 v[2:3], v[2:3], 2, s[0:1]
	global_load_dword v81, v[4:5], off
	global_load_dword v93, v[2:3], off
	v_add_u32_e32 v4, 0x800, v0
	v_add_u32_e32 v2, 0x1400, v0
	v_ashrrev_i32_e32 v5, 31, v4
	v_ashrrev_i32_e32 v3, 31, v2
	v_lshl_add_u64 v[4:5], v[4:5], 2, s[0:1]
	v_lshl_add_u64 v[2:3], v[2:3], 2, s[0:1]
	global_load_dword v82, v[4:5], off
	global_load_dword v94, v[2:3], off
	v_add_u32_e32 v4, 0x880, v0
	v_add_u32_e32 v2, 0x1480, v0
	v_ashrrev_i32_e32 v5, 31, v4
	v_ashrrev_i32_e32 v3, 31, v2
	v_lshl_add_u64 v[4:5], v[4:5], 2, s[0:1]
	v_lshl_add_u64 v[2:3], v[2:3], 2, s[0:1]
	global_load_dword v83, v[4:5], off
	global_load_dword v95, v[2:3], off
	v_add_u32_e32 v4, 0x900, v0
	v_add_u32_e32 v2, 0x1500, v0
	v_ashrrev_i32_e32 v5, 31, v4
	v_ashrrev_i32_e32 v3, 31, v2
	v_lshl_add_u64 v[4:5], v[4:5], 2, s[0:1]
	v_lshl_add_u64 v[2:3], v[2:3], 2, s[0:1]
	global_load_dword v84, v[4:5], off
	global_load_dword v96, v[2:3], off
	v_add_u32_e32 v4, 0x980, v0
	v_add_u32_e32 v2, 0x1580, v0
	v_ashrrev_i32_e32 v5, 31, v4
	v_ashrrev_i32_e32 v3, 31, v2
	v_lshl_add_u64 v[4:5], v[4:5], 2, s[0:1]
	v_lshl_add_u64 v[2:3], v[2:3], 2, s[0:1]
	global_load_dword v85, v[4:5], off
	global_load_dword v97, v[2:3], off
	v_add_u32_e32 v4, 0xc00, v0
	v_add_u32_e32 v2, 0x1800, v0
	v_ashrrev_i32_e32 v5, 31, v4
	v_ashrrev_i32_e32 v3, 31, v2
	v_lshl_add_u64 v[4:5], v[4:5], 2, s[0:1]
	v_lshl_add_u64 v[2:3], v[2:3], 2, s[0:1]
	global_load_dword v86, v[4:5], off
	global_load_dword v98, v[2:3], off
	v_add_u32_e32 v4, 0xc80, v0
	v_add_u32_e32 v2, 0x1880, v0
	v_ashrrev_i32_e32 v5, 31, v4
	v_ashrrev_i32_e32 v3, 31, v2
	v_lshl_add_u64 v[4:5], v[4:5], 2, s[0:1]
	v_lshl_add_u64 v[2:3], v[2:3], 2, s[0:1]
	global_load_dword v87, v[4:5], off
	global_load_dword v99, v[2:3], off
	v_add_u32_e32 v4, 0xd00, v0
	v_add_u32_e32 v2, 0x1900, v0
	v_ashrrev_i32_e32 v5, 31, v4
	v_ashrrev_i32_e32 v3, 31, v2
	v_lshl_add_u64 v[4:5], v[4:5], 2, s[0:1]
	v_lshl_add_u64 v[2:3], v[2:3], 2, s[0:1]
	global_load_dword v88, v[4:5], off
	global_load_dword v100, v[2:3], off
	v_add_u32_e32 v4, 0xd80, v0
	v_add_u32_e32 v2, 0x1980, v0
	v_ashrrev_i32_e32 v5, 31, v4
	v_ashrrev_i32_e32 v3, 31, v2
	v_lshl_add_u64 v[4:5], v[4:5], 2, s[0:1]
	v_lshl_add_u64 v[2:3], v[2:3], 2, s[0:1]
	global_load_dword v89, v[4:5], off
	global_load_dword v101, v[2:3], off
	v_add_u32_e32 v2, 0x1c00, v0
	v_ashrrev_i32_e32 v3, 31, v2
	v_lshl_add_u64 v[2:3], v[2:3], 2, s[0:1]
	global_load_dword v102, v[2:3], off
	v_add_u32_e32 v2, 0x1c80, v0
	v_ashrrev_i32_e32 v3, 31, v2
	v_lshl_add_u64 v[2:3], v[2:3], 2, s[0:1]
	global_load_dword v103, v[2:3], off
	v_add_u32_e32 v2, 0x1d00, v0
	v_add_u32_e32 v0, 0x1d80, v0
	v_ashrrev_i32_e32 v3, 31, v2
	v_ashrrev_i32_e32 v1, 31, v0
	v_lshl_add_u64 v[2:3], v[2:3], 2, s[0:1]
	v_lshl_add_u64 v[0:1], v[0:1], 2, s[0:1]
	global_load_dword v104, v[2:3], off
	global_load_dword v105, v[0:1], off
	s_xor_b32 s3, s38, 7
	s_and_b64 s[0:1], s[36:37], exec
	s_cselect_b32 s3, s3, s38
	s_cmp_eq_u32 s3, 0
	v_readlane_b32 s17, v253, 43
	v_readlane_b32 s18, v253, 44
	v_readlane_b32 s19, v253, 45
	v_readlane_b32 s20, v253, 46
	v_readlane_b32 s21, v253, 47
	v_readlane_b32 s22, v253, 48
	v_readlane_b32 s23, v253, 49
	v_readlane_b32 s24, v253, 50
	v_readlane_b32 s25, v253, 51
	v_readlane_b32 s28, v253, 54
	v_readlane_b32 s29, v253, 55
	v_readlane_b32 s30, v253, 56
	v_readlane_b32 s31, v253, 57
	s_cbranch_scc1 .LBB0_629
	s_lshl_b32 s0, s78, 5
	s_or_b32 s0, s0, s80
	v_readlane_b32 s1, v255, 53
	v_readlane_b32 s50, v253, 14
	v_readlane_b32 s51, v253, 15
	s_or_b32 s0, s0, s1
	s_lshl_b32 s0, s0, 1
	s_or_b32 s0, s0, s81
	s_ashr_i32 s1, s0, 31
	s_lshl_b64 s[40:41], s[0:1], 15
	s_add_u32 s40, s50, s40
	s_addc_u32 s41, s51, s41
	v_readlane_b32 s50, v253, 18
	v_readlane_b32 s51, v253, 19
	s_lshl_b64 s[46:47], s[0:1], 8
	s_add_u32 s46, s50, s46
	s_addc_u32 s47, s51, s47
	s_mov_b32 s44, 0x40000
	s_mov_b32 s45, 0
	s_mov_b32 s48, 0x800
	s_mov_b32 s49, 0
	s_and_b64 s[0:1], s[36:37], exec
	s_cbranch_scc0 .Lfold_fwd
	s_mov_b32 s44, 0xfffc0000
	s_mov_b32 s45, -1
	s_mov_b32 s48, 0xfffff800
	s_mov_b32 s49, -1
.Lfold_fwd:
	v_lshrrev_b32_e32 v192, 6, v235
	v_and_b32_e32 v64, 63, v235
	v_lshlrev_b32_e32 v192, 13, v192
	v_lshl_or_b32 v192, v64, 4, v192
	v_add_u32_e32 v64, 0x1000, v192
	v_lshlrev_b32_e32 v73, 4, v190
	global_load_dwordx4 v[0:3], v192, s[40:41]
	global_load_dwordx4 v[4:7], v192, s[40:41] offset:1024
	global_load_dwordx4 v[8:11], v192, s[40:41] offset:2048
	global_load_dwordx4 v[12:15], v192, s[40:41] offset:3072
	global_load_dwordx4 v[16:19], v64, s[40:41]
	global_load_dwordx4 v[20:23], v64, s[40:41] offset:1024
	global_load_dwordx4 v[24:27], v64, s[40:41] offset:2048
	global_load_dwordx4 v[28:31], v64, s[40:41] offset:3072
	global_load_dwordx4 v[32:35], v73, s[46:47]
	global_load_dwordx4 v[36:39], v73, s[46:47] offset:32
	global_load_dwordx4 v[40:43], v73, s[46:47] offset:64
	global_load_dwordx4 v[44:47], v73, s[46:47] offset:96
	global_load_dwordx4 v[48:51], v73, s[46:47] offset:128
	global_load_dwordx4 v[52:55], v73, s[46:47] offset:160
	global_load_dwordx4 v[56:59], v73, s[46:47] offset:192
	global_load_dwordx4 v[60:63], v73, s[46:47] offset:224
	s_cmp_lt_u32 s3, 2
	s_cbranch_scc1 .Lfold_lastA
	s_add_u32 s40, s40, s44
	s_addc_u32 s41, s41, s45
	s_add_u32 s46, s46, s48
	s_addc_u32 s47, s47, s49
	global_load_dwordx4 v[106:109], v192, s[40:41]
	global_load_dwordx4 v[110:113], v192, s[40:41] offset:1024
	global_load_dwordx4 v[114:117], v192, s[40:41] offset:2048
	global_load_dwordx4 v[118:121], v192, s[40:41] offset:3072
	global_load_dwordx4 v[122:125], v64, s[40:41]
	global_load_dwordx4 v[126:129], v64, s[40:41] offset:1024
	global_load_dwordx4 v[130:133], v64, s[40:41] offset:2048
	global_load_dwordx4 v[134:137], v64, s[40:41] offset:3072
	global_load_dwordx4 v[138:141], v73, s[46:47]
	global_load_dwordx4 v[142:145], v73, s[46:47] offset:32
	global_load_dwordx4 v[146:149], v73, s[46:47] offset:64
	global_load_dwordx4 v[150:153], v73, s[46:47] offset:96
	global_load_dwordx4 v[154:157], v73, s[46:47] offset:128
	global_load_dwordx4 v[158:161], v73, s[46:47] offset:160
	global_load_dwordx4 v[162:165], v73, s[46:47] offset:192
	global_load_dwordx4 v[166:169], v73, s[46:47] offset:224
	s_mov_b32 s39, 2
.Lfold_loop:
	s_waitcnt vmcnt(16)
	v_pk_fma_f32 v[74:75], v[32:33], v[74:75], v[0:1]
	v_pk_fma_f32 v[76:77], v[34:35], v[76:77], v[2:3]
	v_pk_fma_f32 v[78:79], v[36:37], v[78:79], v[4:5]
	v_pk_fma_f32 v[80:81], v[38:39], v[80:81], v[6:7]
	v_pk_fma_f32 v[82:83], v[40:41], v[82:83], v[8:9]
	v_pk_fma_f32 v[84:85], v[42:43], v[84:85], v[10:11]
	v_pk_fma_f32 v[86:87], v[44:45], v[86:87], v[12:13]
	v_pk_fma_f32 v[88:89], v[46:47], v[88:89], v[14:15]
	v_pk_fma_f32 v[90:91], v[48:49], v[90:91], v[16:17]
	v_pk_fma_f32 v[92:93], v[50:51], v[92:93], v[18:19]
	v_pk_fma_f32 v[94:95], v[52:53], v[94:95], v[20:21]
	v_pk_fma_f32 v[96:97], v[54:55], v[96:97], v[22:23]
	v_pk_fma_f32 v[98:99], v[56:57], v[98:99], v[24:25]
	v_pk_fma_f32 v[100:101], v[58:59], v[100:101], v[26:27]
	v_pk_fma_f32 v[102:103], v[60:61], v[102:103], v[28:29]
	v_pk_fma_f32 v[104:105], v[62:63], v[104:105], v[30:31]
	s_cmp_ge_u32 s39, s3
	s_cbranch_scc1 .Lfold_lastB
	s_add_u32 s40, s40, s44
	s_addc_u32 s41, s41, s45
	s_add_u32 s46, s46, s48
	s_addc_u32 s47, s47, s49
	global_load_dwordx4 v[0:3], v192, s[40:41]
	global_load_dwordx4 v[4:7], v192, s[40:41] offset:1024
	global_load_dwordx4 v[8:11], v192, s[40:41] offset:2048
	global_load_dwordx4 v[12:15], v192, s[40:41] offset:3072
	global_load_dwordx4 v[16:19], v64, s[40:41]
	global_load_dwordx4 v[20:23], v64, s[40:41] offset:1024
	global_load_dwordx4 v[24:27], v64, s[40:41] offset:2048
	global_load_dwordx4 v[28:31], v64, s[40:41] offset:3072
	global_load_dwordx4 v[32:35], v73, s[46:47]
	global_load_dwordx4 v[36:39], v73, s[46:47] offset:32
	global_load_dwordx4 v[40:43], v73, s[46:47] offset:64
	global_load_dwordx4 v[44:47], v73, s[46:47] offset:96
	global_load_dwordx4 v[48:51], v73, s[46:47] offset:128
	global_load_dwordx4 v[52:55], v73, s[46:47] offset:160
	global_load_dwordx4 v[56:59], v73, s[46:47] offset:192
	global_load_dwordx4 v[60:63], v73, s[46:47] offset:224
	s_add_i32 s39, s39, 1
	s_waitcnt vmcnt(16)
	v_pk_fma_f32 v[74:75], v[138:139], v[74:75], v[106:107]
	v_pk_fma_f32 v[76:77], v[140:141], v[76:77], v[108:109]
	v_pk_fma_f32 v[78:79], v[142:143], v[78:79], v[110:111]
	v_pk_fma_f32 v[80:81], v[144:145], v[80:81], v[112:113]
	v_pk_fma_f32 v[82:83], v[146:147], v[82:83], v[114:115]
	v_pk_fma_f32 v[84:85], v[148:149], v[84:85], v[116:117]
	v_pk_fma_f32 v[86:87], v[150:151], v[86:87], v[118:119]
	v_pk_fma_f32 v[88:89], v[152:153], v[88:89], v[120:121]
	v_pk_fma_f32 v[90:91], v[154:155], v[90:91], v[122:123]
	v_pk_fma_f32 v[92:93], v[156:157], v[92:93], v[124:125]
	v_pk_fma_f32 v[94:95], v[158:159], v[94:95], v[126:127]
	v_pk_fma_f32 v[96:97], v[160:161], v[96:97], v[128:129]
	v_pk_fma_f32 v[98:99], v[162:163], v[98:99], v[130:131]
	v_pk_fma_f32 v[100:101], v[164:165], v[100:101], v[132:133]
	v_pk_fma_f32 v[102:103], v[166:167], v[102:103], v[134:135]
	v_pk_fma_f32 v[104:105], v[168:169], v[104:105], v[136:137]
	s_cmp_ge_u32 s39, s3
	s_cbranch_scc1 .Lfold_lastA
	s_add_u32 s40, s40, s44
	s_addc_u32 s41, s41, s45
	s_add_u32 s46, s46, s48
	s_addc_u32 s47, s47, s49
	global_load_dwordx4 v[106:109], v192, s[40:41]
	global_load_dwordx4 v[110:113], v192, s[40:41] offset:1024
	global_load_dwordx4 v[114:117], v192, s[40:41] offset:2048
	global_load_dwordx4 v[118:121], v192, s[40:41] offset:3072
	global_load_dwordx4 v[122:125], v64, s[40:41]
	global_load_dwordx4 v[126:129], v64, s[40:41] offset:1024
	global_load_dwordx4 v[130:133], v64, s[40:41] offset:2048
	global_load_dwordx4 v[134:137], v64, s[40:41] offset:3072
	global_load_dwordx4 v[138:141], v73, s[46:47]
	global_load_dwordx4 v[142:145], v73, s[46:47] offset:32
	global_load_dwordx4 v[146:149], v73, s[46:47] offset:64
	global_load_dwordx4 v[150:153], v73, s[46:47] offset:96
	global_load_dwordx4 v[154:157], v73, s[46:47] offset:128
	global_load_dwordx4 v[158:161], v73, s[46:47] offset:160
	global_load_dwordx4 v[162:165], v73, s[46:47] offset:192
	global_load_dwordx4 v[166:169], v73, s[46:47] offset:224
	s_add_i32 s39, s39, 1
	s_branch .Lfold_loop
.Lfold_lastA:
	s_waitcnt vmcnt(0)
	v_pk_fma_f32 v[74:75], v[32:33], v[74:75], v[0:1]
	v_pk_fma_f32 v[76:77], v[34:35], v[76:77], v[2:3]
	v_pk_fma_f32 v[78:79], v[36:37], v[78:79], v[4:5]
	v_pk_fma_f32 v[80:81], v[38:39], v[80:81], v[6:7]
	v_pk_fma_f32 v[82:83], v[40:41], v[82:83], v[8:9]
	v_pk_fma_f32 v[84:85], v[42:43], v[84:85], v[10:11]
	v_pk_fma_f32 v[86:87], v[44:45], v[86:87], v[12:13]
	v_pk_fma_f32 v[88:89], v[46:47], v[88:89], v[14:15]
	v_pk_fma_f32 v[90:91], v[48:49], v[90:91], v[16:17]
	v_pk_fma_f32 v[92:93], v[50:51], v[92:93], v[18:19]
	v_pk_fma_f32 v[94:95], v[52:53], v[94:95], v[20:21]
	v_pk_fma_f32 v[96:97], v[54:55], v[96:97], v[22:23]
	v_pk_fma_f32 v[98:99], v[56:57], v[98:99], v[24:25]
	v_pk_fma_f32 v[100:101], v[58:59], v[100:101], v[26:27]
	v_pk_fma_f32 v[102:103], v[60:61], v[102:103], v[28:29]
	v_pk_fma_f32 v[104:105], v[62:63], v[104:105], v[30:31]
	s_branch .LBB0_629
.Lfold_lastB:
	s_waitcnt vmcnt(0)
	v_pk_fma_f32 v[74:75], v[138:139], v[74:75], v[106:107]
	v_pk_fma_f32 v[76:77], v[140:141], v[76:77], v[108:109]
	v_pk_fma_f32 v[78:79], v[142:143], v[78:79], v[110:111]
	v_pk_fma_f32 v[80:81], v[144:145], v[80:81], v[112:113]
	v_pk_fma_f32 v[82:83], v[146:147], v[82:83], v[114:115]
	v_pk_fma_f32 v[84:85], v[148:149], v[84:85], v[116:117]
	v_pk_fma_f32 v[86:87], v[150:151], v[86:87], v[118:119]
	v_pk_fma_f32 v[88:89], v[152:153], v[88:89], v[120:121]
	v_pk_fma_f32 v[90:91], v[154:155], v[90:91], v[122:123]
	v_pk_fma_f32 v[92:93], v[156:157], v[92:93], v[124:125]
	v_pk_fma_f32 v[94:95], v[158:159], v[94:95], v[126:127]
	v_pk_fma_f32 v[96:97], v[160:161], v[96:97], v[128:129]
	v_pk_fma_f32 v[98:99], v[162:163], v[98:99], v[130:131]
	v_pk_fma_f32 v[100:101], v[164:165], v[100:101], v[132:133]
	v_pk_fma_f32 v[102:103], v[166:167], v[102:103], v[134:135]
	v_pk_fma_f32 v[104:105], v[168:169], v[104:105], v[136:137]

.LBB0_701:
	s_add_i32 s40, s3, 2
	s_cmp_lt_u32 s3, 10
	s_cselect_b64 s[0:1], -1, 0
	s_and_b64 vcc, s[0:1], exec
	s_cselect_b32 s0, s40, 11
	s_lshl_b32 s90, s0, 7
	s_cmp_gt_u32 s0, 7
	v_lshl_add_u64 v[98:99], v[132:133], 0, s[90:91]
	v_lshl_add_u64 v[96:97], v[128:129], 0, s[90:91]
	v_lshl_add_u64 v[98:99], v[98:99], 0, s[82:83]
	s_cselect_b64 s[0:1], -1, 0
	v_cndmask_b32_e64 v121, v97, v99, s[0:1]
	v_cndmask_b32_e64 v120, v96, v98, s[0:1]
	v_lshl_add_u64 v[124:125], v[130:131], 0, s[90:91]
	s_and_b64 s[0:1], s[0:1], exec
	v_add_co_u32_e64 v108, s[0:1], s8, v124
	s_cselect_b32 s90, 0x4000, s88
	s_nop 0
	v_addc_co_u32_e64 v109, s[0:1], 0, v125, s[0:1]
	v_add_co_u32_e64 v116, s[0:1], s76, v124
	v_lshl_add_u64 v[112:113], v[120:121], 0, s[90:91]
	s_nop 0
	v_addc_co_u32_e64 v117, s[0:1], 0, v125, s[0:1]
	global_load_dwordx4 v[96:99], v[120:121], off
	global_load_dwordx4 v[100:103], v[124:125], off
	global_load_dwordx4 v[104:107], v[112:113], off
	v_lshl_add_u64 v[112:113], v[112:113], 0, s[90:91]
	s_cselect_b32 s90, s8, 0x18000
	v_add_co_u32_e64 v124, s[0:1], s9, v124
	v_lshl_add_u64 v[120:121], v[120:121], 0, s[90:91]
	s_nop 0
	v_addc_co_u32_e64 v125, s[0:1], 0, v125, s[0:1]
	global_load_dwordx4 v[108:111], v[108:109], off
	s_nop 0
	global_load_dwordx4 v[112:115], v[112:113], off
	s_nop 0
	global_load_dwordx4 v[116:119], v[116:117], off
	s_nop 0
	global_load_dwordx4 v[120:123], v[120:121], off
	s_nop 0
	global_load_dwordx4 v[124:127], v[124:125], off
	v_add_u32_e32 v141, v135, v137
	ds_read_b128 v[142:145], v141
	v_add_u32_e32 v154, v136, v137
	ds_read_b128 v[146:149], v154 offset:16384
	ds_read_b128 v[150:153], v154 offset:20480
	v_add_u32_e32 v155, v135, v138
	v_add_u32_e32 v156, v136, v138
	v_add_u32_e32 v157, v135, v139
	v_add_u32_e32 v158, v136, v139
	v_add_u32_e32 v159, v135, v140
	s_waitcnt lgkmcnt(1)
	v_mfma_f32_32x32x16_bf16 v[48:63], v[142:145], v[146:149], v[48:63]
	v_add_u32_e32 v160, v136, v140
	s_waitcnt lgkmcnt(0)
	v_mfma_f32_32x32x16_bf16 v[32:47], v[142:145], v[150:153], v[32:47]
	ds_read_b128 v[142:145], v141 offset:4096
	s_waitcnt lgkmcnt(0)
	v_mfma_f32_32x32x16_bf16 v[16:31], v[142:145], v[146:149], v[16:31]
	ds_read_b128 v[146:149], v156 offset:16384
	v_mfma_f32_32x32x16_bf16 v[0:15], v[142:145], v[150:153], v[0:15]
	ds_read_b128 v[142:145], v155
	ds_read_b128 v[150:153], v156 offset:20480
	s_waitcnt lgkmcnt(1)
	v_mfma_f32_32x32x16_bf16 v[48:63], v[142:145], v[146:149], v[48:63]
	s_waitcnt lgkmcnt(0)
	v_mfma_f32_32x32x16_bf16 v[32:47], v[142:145], v[150:153], v[32:47]
	ds_read_b128 v[142:145], v155 offset:4096
	s_waitcnt lgkmcnt(0)
	v_mfma_f32_32x32x16_bf16 v[16:31], v[142:145], v[146:149], v[16:31]
	ds_read_b128 v[146:149], v158 offset:16384
	v_mfma_f32_32x32x16_bf16 v[0:15], v[142:145], v[150:153], v[0:15]
	ds_read_b128 v[142:145], v157
	ds_read_b128 v[150:153], v158 offset:20480
	s_waitcnt lgkmcnt(1)
	v_mfma_f32_32x32x16_bf16 v[48:63], v[142:145], v[146:149], v[48:63]
	s_waitcnt lgkmcnt(0)
	v_mfma_f32_32x32x16_bf16 v[32:47], v[142:145], v[150:153], v[32:47]
	ds_read_b128 v[142:145], v157 offset:4096
	s_waitcnt lgkmcnt(0)
	v_mfma_f32_32x32x16_bf16 v[16:31], v[142:145], v[146:149], v[16:31]
	ds_read_b128 v[146:149], v160 offset:16384
	v_mfma_f32_32x32x16_bf16 v[0:15], v[142:145], v[150:153], v[0:15]
	ds_read_b128 v[142:145], v159
	ds_read_b128 v[150:153], v160 offset:20480
	s_waitcnt lgkmcnt(1)
	v_mfma_f32_32x32x16_bf16 v[48:63], v[142:145], v[146:149], v[48:63]
	s_waitcnt lgkmcnt(0)
	v_mfma_f32_32x32x16_bf16 v[32:47], v[142:145], v[150:153], v[32:47]
	ds_read_b128 v[142:145], v159 offset:4096
	s_waitcnt lgkmcnt(0)
	v_mfma_f32_32x32x16_bf16 v[16:31], v[142:145], v[146:149], v[16:31]
	v_mfma_f32_32x32x16_bf16 v[0:15], v[142:145], v[150:153], v[0:15]
	s_min_u32 s0, s3, 8
	s_lshl_b32 s90, s0, 7
	s_waitcnt vmcnt(11)
	ds_write_b128 v134, v[80:83] offset:32768
	ds_write_b128 v134, v[64:67] offset:49152
	s_waitcnt vmcnt(10)
	ds_write_b128 v134, v[84:87] offset:36864
	ds_write_b128 v134, v[68:71] offset:53248
	s_waitcnt vmcnt(9)
	ds_write_b128 v134, v[88:91] offset:40960
	ds_write_b128 v134, v[72:75] offset:57344
	s_waitcnt vmcnt(8)
	ds_write_b128 v134, v[92:95] offset:45056
	ds_write_b128 v134, v[76:79] offset:61440
	v_lshl_add_u64 v[64:65], v[128:129], 0, s[90:91]
	s_mov_b64 s[0:1], 0x180
	v_lshl_add_u64 v[70:71], v[64:65], 0, s[0:1]
	s_movk_i32 s0, 0xfd80
	v_lshl_add_u64 v[66:67], v[132:133], 0, s[90:91]
	v_lshl_add_u64 v[68:69], v[130:131], 0, s[90:91]
	s_mov_b32 s1, -1
	v_lshl_add_u64 v[72:73], v[66:67], 0, s[0:1]
	v_add_co_u32_e64 v74, s[0:1], s8, v68
	s_cmp_gt_u32 s3, 4
	s_nop 0
	v_addc_co_u32_e64 v75, s[0:1], 0, v69, s[0:1]
	v_add_co_u32_e64 v76, s[0:1], s76, v68
	s_waitcnt lgkmcnt(0)
	s_nop 0
	v_addc_co_u32_e64 v77, s[0:1], 0, v69, s[0:1]
	v_add_co_u32_e64 v78, s[0:1], s9, v68
	s_barrier
	s_nop 0
	v_addc_co_u32_e64 v79, s[0:1], 0, v69, s[0:1]
	s_cselect_b64 s[0:1], -1, 0
	s_nop 0
	v_cndmask_b32_e64 v93, v71, v73, s[0:1]
	v_cndmask_b32_e64 v92, v70, v72, s[0:1]
	s_and_b64 s[0:1], s[0:1], exec
	s_cselect_b32 s90, 0x4000, s88
	v_lshl_add_u64 v[88:89], v[92:93], 0, s[90:91]
	global_load_dwordx4 v[64:67], v[68:69], off offset:384
	s_nop 0
	global_load_dwordx4 v[68:71], v[74:75], off offset:384
	s_nop 0
	global_load_dwordx4 v[72:75], v[76:77], off offset:384
	s_nop 0
	global_load_dwordx4 v[76:79], v[78:79], off offset:384
	s_nop 0
	global_load_dwordx4 v[80:83], v[92:93], off
	global_load_dwordx4 v[84:87], v[88:89], off
	v_lshl_add_u64 v[88:89], v[88:89], 0, s[90:91]
	s_cselect_b32 s90, s8, 0x18000
	v_lshl_add_u64 v[92:93], v[92:93], 0, s[90:91]
	global_load_dwordx4 v[88:91], v[88:89], off
	s_nop 0
	global_load_dwordx4 v[92:95], v[92:93], off
	ds_read_b128 v[142:145], v141 offset:32768
	ds_read_b128 v[146:149], v154 offset:49152
	ds_read_b128 v[150:153], v154 offset:53248
	s_waitcnt lgkmcnt(1)
	v_mfma_f32_32x32x16_bf16 v[48:63], v[142:145], v[146:149], v[48:63]
	s_waitcnt lgkmcnt(0)
	v_mfma_f32_32x32x16_bf16 v[32:47], v[142:145], v[150:153], v[32:47]
	ds_read_b128 v[142:145], v141 offset:36864
	s_waitcnt lgkmcnt(0)
	v_mfma_f32_32x32x16_bf16 v[16:31], v[142:145], v[146:149], v[16:31]
	v_mfma_f32_32x32x16_bf16 v[0:15], v[142:145], v[150:153], v[0:15]
	ds_read_b128 v[142:145], v155 offset:32768
	ds_read_b128 v[146:149], v156 offset:49152
	ds_read_b128 v[150:153], v156 offset:53248
	s_waitcnt lgkmcnt(1)
	v_mfma_f32_32x32x16_bf16 v[48:63], v[142:145], v[146:149], v[48:63]
	s_waitcnt lgkmcnt(0)
	v_mfma_f32_32x32x16_bf16 v[32:47], v[142:145], v[150:153], v[32:47]
	ds_read_b128 v[142:145], v155 offset:36864
	s_waitcnt lgkmcnt(0)
	v_mfma_f32_32x32x16_bf16 v[16:31], v[142:145], v[146:149], v[16:31]
	v_mfma_f32_32x32x16_bf16 v[0:15], v[142:145], v[150:153], v[0:15]
	ds_read_b128 v[142:145], v157 offset:32768
	ds_read_b128 v[146:149], v158 offset:49152
	ds_read_b128 v[150:153], v158 offset:53248
	s_waitcnt lgkmcnt(1)
	v_mfma_f32_32x32x16_bf16 v[48:63], v[142:145], v[146:149], v[48:63]
	s_waitcnt lgkmcnt(0)
	v_mfma_f32_32x32x16_bf16 v[32:47], v[142:145], v[150:153], v[32:47]
	ds_read_b128 v[142:145], v157 offset:36864
	s_waitcnt lgkmcnt(0)
	v_mfma_f32_32x32x16_bf16 v[16:31], v[142:145], v[146:149], v[16:31]
	v_mfma_f32_32x32x16_bf16 v[0:15], v[142:145], v[150:153], v[0:15]
	ds_read_b128 v[142:145], v159 offset:32768
	ds_read_b128 v[146:149], v160 offset:49152
	ds_read_b128 v[150:153], v160 offset:53248
	s_waitcnt lgkmcnt(1)
	v_mfma_f32_32x32x16_bf16 v[48:63], v[142:145], v[146:149], v[48:63]
	s_waitcnt lgkmcnt(0)
	v_mfma_f32_32x32x16_bf16 v[32:47], v[142:145], v[150:153], v[32:47]
	ds_read_b128 v[142:145], v159 offset:36864
	s_waitcnt lgkmcnt(0)
	v_mfma_f32_32x32x16_bf16 v[16:31], v[142:145], v[146:149], v[16:31]
	v_mfma_f32_32x32x16_bf16 v[0:15], v[142:145], v[150:153], v[0:15]
	s_mov_b32 s3, s40
	s_waitcnt vmcnt(15)
	ds_write_b128 v134, v[96:99]
	s_waitcnt vmcnt(14)
	ds_write_b128 v134, v[100:103] offset:16384
	s_waitcnt vmcnt(13)
	ds_write_b128 v134, v[104:107] offset:4096
	s_waitcnt vmcnt(12)
	ds_write_b128 v134, v[108:111] offset:20480
	s_waitcnt vmcnt(11)
	ds_write_b128 v134, v[112:115] offset:8192
	s_waitcnt vmcnt(10)
	ds_write_b128 v134, v[116:119] offset:24576
	s_waitcnt vmcnt(9)
	ds_write_b128 v134, v[120:123] offset:12288
	s_waitcnt vmcnt(8)
	ds_write_b128 v134, v[124:127] offset:28672
	s_waitcnt lgkmcnt(0)
	s_barrier
	s_cbranch_vccnz .LBB0_701
	s_waitcnt vmcnt(7)
	v_mov_b32_e32 v64, v235
	s_mov_b32 s0, 0x7fffc0
	v_lshrrev_b32_e32 v66, 3, v64
	v_lshrrev_b32_e32 v65, 1, v64
	v_and_b32_e32 v66, 4, v66
	v_and_or_b32 v65, v65, s0, v66
	v_and_b32_e32 v64, 0x5f, v64
	v_lshlrev_b32_e32 v65, 9, v65
	v_lshlrev_b32_e32 v64, 2, v64
	v_add3_u32 v64, s13, v65, v64
	ds_write2_b32 v64, v48, v32 offset1:32
	ds_write2_b32 v64, v49, v33 offset0:128 offset1:160
	v_add_u32_e32 v32, 0x400, v64
	ds_write2_b32 v32, v50, v34 offset1:32
	ds_write2_b32 v32, v51, v35 offset0:128 offset1:160
	v_add_u32_e32 v32, 0x1000, v64
	ds_write2_b32 v32, v52, v36 offset1:32
	ds_write2_b32 v32, v53, v37 offset0:128 offset1:160
	v_add_u32_e32 v32, 0x1400, v64
	ds_write2_b32 v32, v54, v38 offset1:32
	ds_write2_b32 v32, v55, v39 offset0:128 offset1:160
	v_add_u32_e32 v32, 0x2000, v64
	ds_write2_b32 v32, v56, v40 offset1:32
	ds_write2_b32 v32, v57, v41 offset0:128 offset1:160
	v_add_u32_e32 v32, 0x2400, v64
	ds_write2_b32 v32, v58, v42 offset1:32
	ds_write2_b32 v32, v59, v43 offset0:128 offset1:160
	v_add_u32_e32 v32, 0x3000, v64
	ds_write2_b32 v32, v60, v44 offset1:32
	ds_write2_b32 v32, v61, v45 offset0:128 offset1:160
	v_add_u32_e32 v32, 0x3400, v64
	ds_write2_b32 v32, v62, v46 offset1:32
	ds_write2_b32 v32, v63, v47 offset0:128 offset1:160
	v_add_u32_e32 v32, 0x4000, v64
	ds_write2_b32 v32, v16, v0 offset1:32
	ds_write2_b32 v32, v17, v1 offset0:128 offset1:160
	v_add_u32_e32 v0, 0x4400, v64
	ds_write2_b32 v0, v18, v2 offset1:32
	ds_write2_b32 v0, v19, v3 offset0:128 offset1:160
	v_add_u32_e32 v0, 0x5000, v64
	ds_write2_b32 v0, v20, v4 offset1:32
	ds_write2_b32 v0, v21, v5 offset0:128 offset1:160
	v_add_u32_e32 v0, 0x5400, v64
	s_lshl_b32 s0, s2, 5
	ds_write2_b32 v0, v22, v6 offset1:32
	ds_write2_b32 v0, v23, v7 offset0:128 offset1:160
	v_add_u32_e32 v0, 0x6000, v64
	s_add_u32 s0, s60, s0
	ds_write2_b32 v0, v24, v8 offset1:32
	ds_write2_b32 v0, v25, v9 offset0:128 offset1:160
	v_add_u32_e32 v0, 0x6400, v64
	s_mul_i32 s90, s2, 0x3000
	s_addc_u32 s1, s61, 0
	s_lshl_b32 s2, s2, 6
	ds_write2_b32 v0, v26, v10 offset1:32
	ds_write2_b32 v0, v27, v11 offset0:128 offset1:160
	v_add_u32_e32 v0, 0x7000, v64
	s_add_u32 s2, s36, s2
	ds_write2_b32 v0, v28, v12 offset1:32
	ds_write2_b32 v0, v29, v13 offset0:128 offset1:160
	v_add_u32_e32 v0, 0x7400, v64
	s_addc_u32 s3, s37, 0
	s_mov_b32 s40, 0
	ds_write2_b32 v0, v30, v14 offset1:32
	ds_write2_b32 v0, v31, v15 offset0:128 offset1:160
	v_lshlrev_b32_e32 v228, 3, v235
	v_and_b32_e32 v226, 0x78, v228
	v_or_b32_e32 v226, s38, v226
	v_lshrrev_b32_e32 v226, 4, v226
	v_ashrrev_i32_e32 v224, 4, v235
	v_add_u32_e32 v224, s39, v224
	v_lshl_or_b32 v224, v224, 5, v226
	v_ashrrev_i32_e32 v225, 31, v224
	v_lshl_add_u64 v[224:225], s[90:91], 0, v[224:225]
	v_lshlrev_b64 v[224:225], 5, v[224:225]
	v_lshl_add_u64 v[224:225], s[68:69], 0, v[224:225]
	v_and_b32_e32 v228, 8, v228
	v_lshlrev_b32_e32 v226, 1, v228
	v_mov_b32_e32 v227, 0
	v_lshl_add_u64 v[224:225], v[224:225], 0, v[226:227]
	v_lshlrev_b32_e32 v228, 2, v228
	global_load_dwordx4 v[216:219], v228, s[2:3] offset:16
	global_load_dwordx4 v[212:215], v228, s[2:3]
	global_load_dwordx4 v[220:223], v[224:225], off
	s_mov_b32 s14, 0x4000
	s_mov_b32 s15, 0
	s_waitcnt lgkmcnt(0)
	s_barrier
	s_waitcnt vmcnt(0)
.LBB0_703:
	s_nop 0
	v_mov_b32_e32 v0, v235
	v_mov_b32_e32 v1, v235
	s_add_i32 s41, s39, s40
	v_lshlrev_b32_e32 v1, 3, v1
	v_and_b32_e32 v2, 0x78, v1
	v_ashrrev_i32_e32 v0, 4, v0
	v_lshlrev_b32_e32 v4, 2, v2
	v_or_b32_e32 v2, s38, v2
	v_add_lshl_u32 v3, s40, v0, 9
	v_add_u32_e32 v0, s41, v0
	v_lshrrev_b32_e32 v2, 4, v2
	v_lshl_or_b32 v16, v0, 5, v2
	v_ashrrev_i32_e32 v17, 31, v16
	v_and_b32_e32 v5, 8, v1
	v_lshlrev_b32_e32 v192, 1, v5
	v_add3_u32 v4, s13, v4, v3
	s_add_i32 s40, s40, 16
	s_cmpk_eq_i32 s40, 0x80
	s_waitcnt vmcnt(1)
	v_lshlrev_b32_e32 v18, 16, v220
	v_and_b32_e32 v19, 0xffff0000, v220
	v_lshlrev_b32_e32 v20, 16, v221
	v_and_b32_e32 v21, 0xffff0000, v221
	v_lshlrev_b32_e32 v22, 16, v222
	v_and_b32_e32 v23, 0xffff0000, v222
	v_lshlrev_b32_e32 v24, 16, v223
	v_and_b32_e32 v25, 0xffff0000, v223
	s_cbranch_scc1 .Ls5y_nopf
	v_lshl_add_u64 v[224:225], s[14:15], 0, v[224:225]
	global_load_dwordx4 v[220:223], v[224:225], off
.Ls5y_nopf:
	ds_read_b128 v[0:3], v4
	ds_read_b128 v[4:7], v4 offset:16
	s_waitcnt lgkmcnt(0)
	v_pk_fma_f32 v[4:5], v[216:217], v[22:23], v[4:5]
	v_pk_fma_f32 v[0:1], v[212:213], v[18:19], v[0:1]
	v_mul_f32_e32 v8, 0x3d372713, v4
	v_mul_f32_e32 v12, 0x3d372713, v0
	v_mul_f32_e32 v13, 0x3d372713, v1
	v_mul_f32_e32 v12, v0, v12
	v_mul_f32_e32 v13, v1, v13
	v_fma_f32 v12, v0, v12, v0
	v_fma_f32 v13, v1, v13, v1
	v_mul_f32_e32 v9, 0x3d372713, v5
	v_mul_f32_e32 v12, 0x3f4c422a, v12
	v_mul_f32_e32 v13, 0x3f4c422a, v13
	v_mul_f32_e32 v8, v4, v8
	v_mul_f32_e32 v9, v5, v9
	v_mul_f32_e32 v12, 0x4038aa3b, v12
	v_mul_f32_e32 v13, 0x4038aa3b, v13
	v_fma_f32 v8, v4, v8, v4
	v_fma_f32 v9, v5, v9, v5
	v_exp_f32_e32 v12, v12
	v_exp_f32_e32 v13, v13
	v_mul_f32_e32 v8, 0x3f4c422a, v8
	v_mul_f32_e32 v9, 0x3f4c422a, v9
	v_mul_f32_e32 v8, 0x4038aa3b, v8
	v_mul_f32_e32 v9, 0x4038aa3b, v9
	v_exp_f32_e32 v8, v8
	v_exp_f32_e32 v9, v9
	v_add_f32_e32 v12, 1.0, v12
	v_add_f32_e32 v13, 1.0, v13
	v_rcp_f32_e32 v12, v12
	v_rcp_f32_e32 v13, v13
	v_add_f32_e32 v8, 1.0, v8
	v_add_f32_e32 v9, 1.0, v9
	v_rcp_f32_e32 v8, v8
	v_rcp_f32_e32 v9, v9
	v_pk_fma_f32 v[12:13], v[12:13], 2.0, 1.0 op_sel_hi:[1,0,0] neg_lo:[1,0,0] neg_hi:[1,0,0]
	v_pk_mul_f32 v[0:1], v[0:1], 0.5 op_sel_hi:[1,0]
	v_pk_add_f32 v[12:13], v[12:13], 1.0 op_sel_hi:[1,0]
	v_pk_fma_f32 v[2:3], v[214:215], v[20:21], v[2:3]
	v_pk_mul_f32 v[0:1], v[0:1], v[12:13]
	v_mul_f32_e32 v12, 0x3d372713, v2
	v_mul_f32_e32 v13, 0x3d372713, v3
	v_pk_fma_f32 v[8:9], v[8:9], 2.0, 1.0 op_sel_hi:[1,0,0] neg_lo:[1,0,0] neg_hi:[1,0,0]
	v_mul_f32_e32 v12, v2, v12
	v_mul_f32_e32 v13, v3, v13
	v_pk_mul_f32 v[4:5], v[4:5], 0.5 op_sel_hi:[1,0]
	v_pk_add_f32 v[8:9], v[8:9], 1.0 op_sel_hi:[1,0]
	v_pk_fma_f32 v[6:7], v[218:219], v[24:25], v[6:7]
	v_fma_f32 v12, v2, v12, v2
	v_fma_f32 v13, v3, v13, v3
	v_pk_mul_f32 v[4:5], v[4:5], v[8:9]
	v_mul_f32_e32 v8, 0x3d372713, v6
	v_mul_f32_e32 v9, 0x3d372713, v7
	v_mul_f32_e32 v12, 0x3f4c422a, v12
	v_mul_f32_e32 v13, 0x3f4c422a, v13
	v_mul_f32_e32 v8, v6, v8
	v_mul_f32_e32 v9, v7, v9
	v_mul_f32_e32 v12, 0x4038aa3b, v12
	v_mul_f32_e32 v13, 0x4038aa3b, v13
	v_fma_f32 v8, v6, v8, v6
	v_fma_f32 v9, v7, v9, v7
	v_exp_f32_e32 v12, v12
	v_exp_f32_e32 v13, v13
	v_mul_f32_e32 v8, 0x3f4c422a, v8
	v_mul_f32_e32 v9, 0x3f4c422a, v9
	v_mul_f32_e32 v8, 0x4038aa3b, v8
	v_mul_f32_e32 v9, 0x4038aa3b, v9
	v_exp_f32_e32 v8, v8
	v_exp_f32_e32 v9, v9
	v_add_f32_e32 v12, 1.0, v12
	v_add_f32_e32 v13, 1.0, v13
	v_rcp_f32_e32 v12, v12
	v_rcp_f32_e32 v13, v13
	v_add_f32_e32 v8, 1.0, v8
	v_add_f32_e32 v9, 1.0, v9
	v_rcp_f32_e32 v8, v8
	v_rcp_f32_e32 v9, v9
	v_pk_fma_f32 v[12:13], v[12:13], 2.0, 1.0 op_sel_hi:[1,0,0] neg_lo:[1,0,0] neg_hi:[1,0,0]
	v_pk_mul_f32 v[2:3], v[2:3], 0.5 op_sel_hi:[1,0]
	v_pk_add_f32 v[12:13], v[12:13], 1.0 op_sel_hi:[1,0]
	v_pk_fma_f32 v[8:9], v[8:9], 2.0, 1.0 op_sel_hi:[1,0,0] neg_lo:[1,0,0] neg_hi:[1,0,0]
	v_pk_mul_f32 v[2:3], v[2:3], v[12:13]
	v_pk_mul_f32 v[6:7], v[6:7], 0.5 op_sel_hi:[1,0]
	v_pk_add_f32 v[8:9], v[8:9], 1.0 op_sel_hi:[1,0]
	v_cvt_pk_bf16_f32 v0, v0, v1
	v_cvt_pk_bf16_f32 v1, v2, v3
	v_cvt_pk_bf16_f32 v2, v4, v5
	v_lshlrev_b64 v[4:5], 10, v[16:17]
	v_pk_mul_f32 v[6:7], v[6:7], v[8:9]
	v_lshl_add_u64 v[4:5], s[0:1], 0, v[4:5]
	v_cvt_pk_bf16_f32 v3, v6, v7
	v_lshl_add_u64 v[4:5], v[4:5], 0, v[192:193]
	global_store_dwordx4 v[4:5], v[0:3], off
	s_cbranch_scc0 .LBB0_703
	v_readlane_b32 s0, v255, 17
	s_add_i32 s12, s12, s0
	s_cmp_gt_u32 s12, 47
	s_barrier
	s_cbranch_scc0 .LBB0_700
	v_readlane_b32 s24, v253, 18
	v_readlane_b32 s26, v253, 20
	v_readlane_b32 s27, v253, 21
	v_readlane_b32 s28, v253, 22
	v_readlane_b32 s29, v253, 23
	v_readlane_b32 s25, v253, 19
	v_readlane_b32 s30, v253, 24
	v_readlane_b32 s31, v253, 25

	.amdhsa_kernel _Z6k_mega6Params
		.amdhsa_group_segment_fixed_size 0
		.amdhsa_private_segment_fixed_size 0
		.amdhsa_kernarg_size 688
		.amdhsa_user_sgpr_count 2
		.amdhsa_user_sgpr_dispatch_ptr 0
		.amdhsa_user_sgpr_queue_ptr 0
		.amdhsa_user_sgpr_kernarg_segment_ptr 1
		.amdhsa_user_sgpr_dispatch_id 0
		.amdhsa_user_sgpr_kernarg_preload_length 0
		.amdhsa_user_sgpr_kernarg_preload_offset 0
		.amdhsa_user_sgpr_private_segment_size 0
		.amdhsa_uses_dynamic_stack 0
		.amdhsa_enable_private_segment 0
		.amdhsa_system_sgpr_workgroup_id_x 1
		.amdhsa_system_sgpr_workgroup_id_y 0
		.amdhsa_system_sgpr_workgroup_id_z 0
		.amdhsa_system_sgpr_workgroup_info 0
		.amdhsa_system_vgpr_workitem_id 2
		.amdhsa_next_free_vgpr 256
		.amdhsa_next_free_sgpr 100
		.amdhsa_accum_offset 256
		.amdhsa_reserve_vcc 1
		.amdhsa_float_round_mode_32 0
		.amdhsa_float_round_mode_16_64 0
		.amdhsa_float_denorm_mode_32 3
		.amdhsa_float_denorm_mode_16_64 3
		.amdhsa_dx10_clamp 1
		.amdhsa_ieee_mode 1
		.amdhsa_fp16_overflow 0
		.amdhsa_tg_split 0
		.amdhsa_exception_fp_ieee_invalid_op 0
		.amdhsa_exception_fp_denorm_src 0
		.amdhsa_exception_fp_ieee_div_zero 0
		.amdhsa_exception_fp_ieee_overflow 0
		.amdhsa_exception_fp_ieee_underflow 0
		.amdhsa_exception_fp_ieee_inexact 0
		.amdhsa_exception_int_div_zero 0
	.end_amdhsa_kernel

amdhsa.kernels:
  - .agpr_count:     0
    .args:
      - .offset:         0
        .size:           432
        .value_kind:     by_value
      - .offset:         432
        .size:           4
        .value_kind:     hidden_block_count_x
      - .offset:         436
        .size:           4
        .value_kind:     hidden_block_count_y
      - .offset:         440
        .size:           4
        .value_kind:     hidden_block_count_z
      - .offset:         444
        .size:           2
        .value_kind:     hidden_group_size_x
      - .offset:         446
        .size:           2
        .value_kind:     hidden_group_size_y
      - .offset:         448
        .size:           2
        .value_kind:     hidden_group_size_z
      - .offset:         450
        .size:           2
        .value_kind:     hidden_remainder_x
      - .offset:         452
        .size:           2
        .value_kind:     hidden_remainder_y
      - .offset:         454
        .size:           2
        .value_kind:     hidden_remainder_z
      - .offset:         472
        .size:           8
        .value_kind:     hidden_global_offset_x
      - .offset:         480
        .size:           8
        .value_kind:     hidden_global_offset_y
      - .offset:         488
        .size:           8
        .value_kind:     hidden_global_offset_z
      - .offset:         496
        .size:           2
        .value_kind:     hidden_grid_dims
      - .offset:         520
        .size:           8
        .value_kind:     hidden_multigrid_sync_arg
      - .offset:         552
        .size:           4
        .value_kind:     hidden_dynamic_lds_size
    .group_segment_fixed_size: 0
    .kernarg_segment_align: 8
    .kernarg_segment_size: 688
    .language:       OpenCL C
    .language_version:
      - 2
      - 0
    .max_flat_workgroup_size: 512
    .name:           _Z6k_mega6Params
    .private_segment_fixed_size: 0
    .sgpr_count:     106
    .sgpr_spill_count: 184
    .symbol:         _Z6k_mega6Params.kd
    .uniform_work_group_size: 1
    .uses_dynamic_stack: false
    .vgpr_count:     256
    .vgpr_spill_count: 0
    .wavefront_size: 64
